# XCC-local barriers: L1 invalidate issued with the arrive atomic (no loads can refill L1 before the release is seen) instead of after the release
# speedup vs baseline: 1.0344x; 1.0088x over previous
; __device__ __forceinline__ unsigned xb_ld(unsigned* p)              { return __hip_atomic_load(p, __ATOMIC_RELAXED, __HIP_MEMORY_SCOPE_AGENT); }
; __device__ __forceinline__ unsigned xb_add(unsigned* p, unsigned v) { return __hip_atomic_fetch_add(p, v, __ATOMIC_RELAXED, __HIP_MEMORY_SCOPE_AGENT); }
; #define XB_SPIN(cond, bar) do { unsigned _sp = 0; while (cond) { __builtin_amdgcn_s_sleep(1); \
;     if ((++_sp & 255u) == 0u) { if (xb_ld(&(bar)[XB_TMO])) break; if (_sp > XB_SPIN_CAP) { atomicAdd(&(bar)[XB_TMO], 1u); break; } } } } while (0)
; __device__ __forceinline__ void xcc_local_barrier(unsigned* bar2, unsigned x, unsigned nloc, unsigned* tmobar) {
;     ...
;     if (threadIdx.x == 0) {
;         const unsigned old = xb_add(&bar2[XB_XSUB(x)], 1u);
;         const unsigned gen = old / nloc;
;         if (old + 1u == (gen + 1u) * nloc) (void)xb_add(&bar2[XB_XGEN(x)], 1u);
;         else XB_SPIN(xb_ld(&bar2[XB_XGEN(x)]) == gen, tmobar);
.LBB0_482:
	s_or_b64 exec, exec, s[40:41]
	buffer_inv sc1
	s_waitcnt vmcnt(0)
	v_readfirstlane_b32 s24, v4
	v_cvt_f32_u32_e32 v4, v2
	v_sub_u32_e32 v5, 0, v2
	v_add_u32_e32 v3, s24, v3
	v_readlane_b32 s6, v239, 58
	v_rcp_iflag_f32_e32 v4, v4
	v_readlane_b32 s7, v239, 59
	s_mov_b64 s[42:43], -1
	v_mul_f32_e32 v4, 0x4f7ffffe, v4
	v_cvt_u32_f32_e32 v4, v4
	v_mul_lo_u32 v5, v5, v4
	v_mul_hi_u32 v5, v4, v5
	v_add_u32_e32 v4, v4, v5
	v_mul_hi_u32 v4, v3, v4
	v_mul_lo_u32 v5, v4, v2
	v_sub_u32_e32 v5, v3, v5
	v_cmp_ge_u32_e32 vcc, v5, v2
	v_add_u32_e32 v6, 1, v4
	v_add_u32_e32 v3, 1, v3
	v_cndmask_b32_e32 v4, v4, v6, vcc
	v_sub_u32_e32 v6, v5, v2
	v_cndmask_b32_e32 v5, v5, v6, vcc
	v_cmp_ge_u32_e32 vcc, v5, v2
	v_add_u32_e32 v5, 1, v4
	s_nop 0
	v_cndmask_b32_e32 v4, v4, v5, vcc
	v_mul_lo_u32 v5, v2, v4
	v_add_u32_e32 v2, v5, v2
	v_cmp_ne_u32_e32 vcc, v3, v2
	v_mov_b64_e32 v[2:3], s[6:7]
	s_and_saveexec_b64 s[40:41], vcc
	s_cbranch_execz .LBB0_494
	v_readlane_b32 s6, v239, 58
	v_readlane_b32 s7, v239, 59
	s_mov_b64 s[44:45], 0
	s_nop 3
	global_load_dword v2, v66, s[6:7] sc1
	s_waitcnt vmcnt(0)
	v_cmp_eq_u32_e32 vcc, v2, v4
	s_and_saveexec_b64 s[42:43], vcc
	s_cbranch_execz .LBB0_493
	s_mov_b32 s24, 1
	s_branch .LBB0_486

; __device__ __forceinline__ void xcc_local_barrier(unsigned* bar2, unsigned x, unsigned nloc, unsigned* tmobar) {
;     ...
;         __builtin_amdgcn_fence(__ATOMIC_ACQUIRE, "agent");
;         asm volatile("s_waitcnt vmcnt(0)" ::: "memory");
.LBB0_496:
	s_or_b64 exec, exec, s[40:41]
	s_waitcnt vmcnt(0)
	s_waitcnt vmcnt(0)

; __device__ __forceinline__ unsigned xb_ld(unsigned* p)              { return __hip_atomic_load(p, __ATOMIC_RELAXED, __HIP_MEMORY_SCOPE_AGENT); }
; __device__ __forceinline__ unsigned xb_add(unsigned* p, unsigned v) { return __hip_atomic_fetch_add(p, v, __ATOMIC_RELAXED, __HIP_MEMORY_SCOPE_AGENT); }
; #define XB_SPIN(cond, bar) do { unsigned _sp = 0; while (cond) { __builtin_amdgcn_s_sleep(1); \
;     if ((++_sp & 255u) == 0u) { if (xb_ld(&(bar)[XB_TMO])) break; if (_sp > XB_SPIN_CAP) { atomicAdd(&(bar)[XB_TMO], 1u); break; } } } } while (0)
; __device__ __forceinline__ void xcc_local_barrier(unsigned* bar2, unsigned x, unsigned nloc, unsigned* tmobar) {
;     ...
;     if (threadIdx.x == 0) {
;         const unsigned old = xb_add(&bar2[XB_XSUB(x)], 1u);
;         const unsigned gen = old / nloc;
;         if (old + 1u == (gen + 1u) * nloc) (void)xb_add(&bar2[XB_XGEN(x)], 1u);
;         else XB_SPIN(xb_ld(&bar2[XB_XGEN(x)]) == gen, tmobar);
.LBB0_616:
	s_or_b64 exec, exec, s[42:43]
	buffer_inv sc1
	s_waitcnt vmcnt(0)
	v_readfirstlane_b32 s24, v4
	v_cvt_f32_u32_e32 v4, v2
	v_sub_u32_e32 v5, 0, v2
	v_add_u32_e32 v3, s24, v3
	v_readlane_b32 s6, v239, 58
	v_rcp_iflag_f32_e32 v4, v4
	v_readlane_b32 s7, v239, 59
	s_mov_b64 s[44:45], -1
	v_mul_f32_e32 v4, 0x4f7ffffe, v4
	v_cvt_u32_f32_e32 v4, v4
	v_mul_lo_u32 v5, v5, v4
	v_mul_hi_u32 v5, v4, v5
	v_add_u32_e32 v4, v4, v5
	v_mul_hi_u32 v4, v3, v4
	v_mul_lo_u32 v5, v4, v2
	v_sub_u32_e32 v5, v3, v5
	v_cmp_ge_u32_e32 vcc, v5, v2
	v_add_u32_e32 v6, 1, v4
	v_add_u32_e32 v3, 1, v3
	v_cndmask_b32_e32 v4, v4, v6, vcc
	v_sub_u32_e32 v6, v5, v2
	v_cndmask_b32_e32 v5, v5, v6, vcc
	v_cmp_ge_u32_e32 vcc, v5, v2
	v_add_u32_e32 v5, 1, v4
	s_nop 0
	v_cndmask_b32_e32 v4, v4, v5, vcc
	v_mul_lo_u32 v5, v2, v4
	v_add_u32_e32 v2, v5, v2
	v_cmp_ne_u32_e32 vcc, v3, v2
	v_mov_b64_e32 v[2:3], s[6:7]
	s_and_saveexec_b64 s[42:43], vcc
	s_cbranch_execz .LBB0_628
	v_readlane_b32 s6, v239, 58
	v_readlane_b32 s7, v239, 59
	s_mov_b64 s[46:47], 0
	s_nop 3
	global_load_dword v2, v66, s[6:7] sc1
	s_waitcnt vmcnt(0)
	v_cmp_eq_u32_e32 vcc, v2, v4
	s_and_saveexec_b64 s[44:45], vcc
	s_cbranch_execz .LBB0_627
	s_mov_b32 s24, 1
	s_branch .LBB0_620

; __device__ __forceinline__ void xcc_local_barrier(unsigned* bar2, unsigned x, unsigned nloc, unsigned* tmobar) {
;     ...
;         __builtin_amdgcn_fence(__ATOMIC_ACQUIRE, "agent");
;         asm volatile("s_waitcnt vmcnt(0)" ::: "memory");
.LBB0_630:
	s_or_b64 exec, exec, s[42:43]
	s_waitcnt vmcnt(0)
	s_waitcnt vmcnt(0)

; __device__ __forceinline__ unsigned xb_ld(unsigned* p)              { return __hip_atomic_load(p, __ATOMIC_RELAXED, __HIP_MEMORY_SCOPE_AGENT); }
; __device__ __forceinline__ unsigned xb_add(unsigned* p, unsigned v) { return __hip_atomic_fetch_add(p, v, __ATOMIC_RELAXED, __HIP_MEMORY_SCOPE_AGENT); }
; #define XB_SPIN(cond, bar) do { unsigned _sp = 0; while (cond) { __builtin_amdgcn_s_sleep(1); \
;     if ((++_sp & 255u) == 0u) { if (xb_ld(&(bar)[XB_TMO])) break; if (_sp > XB_SPIN_CAP) { atomicAdd(&(bar)[XB_TMO], 1u); break; } } } } while (0)
; __device__ __forceinline__ void xcc_local_barrier(unsigned* bar2, unsigned x, unsigned nloc, unsigned* tmobar) {
;     ...
;     if (threadIdx.x == 0) {
;         const unsigned old = xb_add(&bar2[XB_XSUB(x)], 1u);
;         const unsigned gen = old / nloc;
;         if (old + 1u == (gen + 1u) * nloc) (void)xb_add(&bar2[XB_XGEN(x)], 1u);
;         else XB_SPIN(xb_ld(&bar2[XB_XGEN(x)]) == gen, tmobar);
.LBB0_725:
	s_or_b64 exec, exec, s[46:47]
	buffer_inv sc1
	s_waitcnt vmcnt(0)
	v_readfirstlane_b32 s24, v4
	v_cvt_f32_u32_e32 v4, v2
	v_sub_u32_e32 v5, 0, v2
	v_add_u32_e32 v3, s24, v3
	v_readlane_b32 s6, v239, 58
	v_rcp_iflag_f32_e32 v4, v4
	v_readlane_b32 s7, v239, 59
	s_mov_b64 s[48:49], -1
	v_mul_f32_e32 v4, 0x4f7ffffe, v4
	v_cvt_u32_f32_e32 v4, v4
	v_mul_lo_u32 v5, v5, v4
	v_mul_hi_u32 v5, v4, v5
	v_add_u32_e32 v4, v4, v5
	v_mul_hi_u32 v4, v3, v4
	v_mul_lo_u32 v5, v4, v2
	v_sub_u32_e32 v5, v3, v5
	v_cmp_ge_u32_e32 vcc, v5, v2
	v_add_u32_e32 v6, 1, v4
	v_add_u32_e32 v3, 1, v3
	v_cndmask_b32_e32 v4, v4, v6, vcc
	v_sub_u32_e32 v6, v5, v2
	v_cndmask_b32_e32 v5, v5, v6, vcc
	v_cmp_ge_u32_e32 vcc, v5, v2
	v_add_u32_e32 v5, 1, v4
	s_nop 0
	v_cndmask_b32_e32 v4, v4, v5, vcc
	v_mul_lo_u32 v5, v2, v4
	v_add_u32_e32 v2, v5, v2
	v_cmp_ne_u32_e32 vcc, v3, v2
	v_mov_b64_e32 v[2:3], s[6:7]
	s_and_saveexec_b64 s[46:47], vcc
	s_cbranch_execz .LBB0_737
	v_readlane_b32 s6, v239, 58
	v_readlane_b32 s7, v239, 59
	s_mov_b64 s[50:51], 0
	s_nop 3
	global_load_dword v2, v66, s[6:7] sc1
	s_waitcnt vmcnt(0)
	v_cmp_eq_u32_e32 vcc, v2, v4
	s_and_saveexec_b64 s[48:49], vcc
	s_cbranch_execz .LBB0_736
	s_mov_b32 s24, 1
	s_branch .LBB0_729

; __device__ __forceinline__ void xcc_local_barrier(unsigned* bar2, unsigned x, unsigned nloc, unsigned* tmobar) {
;     ...
;         __builtin_amdgcn_fence(__ATOMIC_ACQUIRE, "agent");
;         asm volatile("s_waitcnt vmcnt(0)" ::: "memory");
.LBB0_739:
	s_or_b64 exec, exec, s[46:47]
	s_waitcnt vmcnt(0)
	s_waitcnt vmcnt(0)

; __device__ __forceinline__ unsigned xb_ld(unsigned* p)              { return __hip_atomic_load(p, __ATOMIC_RELAXED, __HIP_MEMORY_SCOPE_AGENT); }
; __device__ __forceinline__ unsigned xb_add(unsigned* p, unsigned v) { return __hip_atomic_fetch_add(p, v, __ATOMIC_RELAXED, __HIP_MEMORY_SCOPE_AGENT); }
; #define XB_SPIN(cond, bar) do { unsigned _sp = 0; while (cond) { __builtin_amdgcn_s_sleep(1); \
;     if ((++_sp & 255u) == 0u) { if (xb_ld(&(bar)[XB_TMO])) break; if (_sp > XB_SPIN_CAP) { atomicAdd(&(bar)[XB_TMO], 1u); break; } } } } while (0)
; __device__ __forceinline__ void xcc_local_barrier(unsigned* bar2, unsigned x, unsigned nloc, unsigned* tmobar) {
;     ...
;     if (threadIdx.x == 0) {
;         const unsigned old = xb_add(&bar2[XB_XSUB(x)], 1u);
;         const unsigned gen = old / nloc;
;         if (old + 1u == (gen + 1u) * nloc) (void)xb_add(&bar2[XB_XGEN(x)], 1u);
;         else XB_SPIN(xb_ld(&bar2[XB_XGEN(x)]) == gen, tmobar);
.LBB0_878:
	s_or_b64 exec, exec, s[44:45]
	buffer_inv sc1
	s_waitcnt vmcnt(0)
	v_readfirstlane_b32 s24, v4
	v_cvt_f32_u32_e32 v4, v2
	v_sub_u32_e32 v5, 0, v2
	v_add_u32_e32 v3, s24, v3
	v_readlane_b32 s6, v239, 58
	v_rcp_iflag_f32_e32 v4, v4
	v_readlane_b32 s7, v239, 59
	s_mov_b64 s[46:47], -1
	v_mul_f32_e32 v4, 0x4f7ffffe, v4
	v_cvt_u32_f32_e32 v4, v4
	v_mul_lo_u32 v5, v5, v4
	v_mul_hi_u32 v5, v4, v5
	v_add_u32_e32 v4, v4, v5
	v_mul_hi_u32 v4, v3, v4
	v_mul_lo_u32 v5, v4, v2
	v_sub_u32_e32 v5, v3, v5
	v_cmp_ge_u32_e32 vcc, v5, v2
	v_add_u32_e32 v6, 1, v4
	v_add_u32_e32 v3, 1, v3
	v_cndmask_b32_e32 v4, v4, v6, vcc
	v_sub_u32_e32 v6, v5, v2
	v_cndmask_b32_e32 v5, v5, v6, vcc
	v_cmp_ge_u32_e32 vcc, v5, v2
	v_add_u32_e32 v5, 1, v4
	s_nop 0
	v_cndmask_b32_e32 v4, v4, v5, vcc
	v_mul_lo_u32 v5, v2, v4
	v_add_u32_e32 v2, v5, v2
	v_cmp_ne_u32_e32 vcc, v3, v2
	v_mov_b64_e32 v[2:3], s[6:7]
	s_and_saveexec_b64 s[44:45], vcc
	s_cbranch_execz .LBB0_890
	v_readlane_b32 s6, v239, 58
	v_readlane_b32 s7, v239, 59
	s_mov_b64 s[48:49], 0
	s_nop 3
	global_load_dword v2, v66, s[6:7] sc1
	s_waitcnt vmcnt(0)
	v_cmp_eq_u32_e32 vcc, v2, v4
	s_and_saveexec_b64 s[46:47], vcc
	s_cbranch_execz .LBB0_889
	s_mov_b32 s24, 1
	s_branch .LBB0_882

; __device__ __forceinline__ void xcc_local_barrier(unsigned* bar2, unsigned x, unsigned nloc, unsigned* tmobar) {
;     ...
;         __builtin_amdgcn_fence(__ATOMIC_ACQUIRE, "agent");
;         asm volatile("s_waitcnt vmcnt(0)" ::: "memory");
.LBB0_892:
	s_or_b64 exec, exec, s[44:45]
	s_waitcnt vmcnt(0)
	s_waitcnt vmcnt(0)

; __device__ __forceinline__ unsigned xb_ld(unsigned* p)              { return __hip_atomic_load(p, __ATOMIC_RELAXED, __HIP_MEMORY_SCOPE_AGENT); }
; __device__ __forceinline__ unsigned xb_add(unsigned* p, unsigned v) { return __hip_atomic_fetch_add(p, v, __ATOMIC_RELAXED, __HIP_MEMORY_SCOPE_AGENT); }
; #define XB_SPIN(cond, bar) do { unsigned _sp = 0; while (cond) { __builtin_amdgcn_s_sleep(1); \
;     if ((++_sp & 255u) == 0u) { if (xb_ld(&(bar)[XB_TMO])) break; if (_sp > XB_SPIN_CAP) { atomicAdd(&(bar)[XB_TMO], 1u); break; } } } } while (0)
; __device__ __forceinline__ void xcc_local_barrier(unsigned* bar2, unsigned x, unsigned nloc, unsigned* tmobar) {
;     ...
;     if (threadIdx.x == 0) {
;         const unsigned old = xb_add(&bar2[XB_XSUB(x)], 1u);
;         const unsigned gen = old / nloc;
;         if (old + 1u == (gen + 1u) * nloc) (void)xb_add(&bar2[XB_XGEN(x)], 1u);
;         else XB_SPIN(xb_ld(&bar2[XB_XGEN(x)]) == gen, tmobar);
.LBB0_1048:
	s_or_b64 exec, exec, s[38:39]
	buffer_inv sc1
	s_waitcnt vmcnt(0)
	v_readfirstlane_b32 s23, v4
	v_cvt_f32_u32_e32 v4, v2
	v_sub_u32_e32 v5, 0, v2
	v_add_u32_e32 v3, s23, v3
	v_readlane_b32 s6, v239, 58
	v_rcp_iflag_f32_e32 v4, v4
	v_readlane_b32 s7, v239, 59
	s_mov_b64 s[40:41], -1
	v_mul_f32_e32 v4, 0x4f7ffffe, v4
	v_cvt_u32_f32_e32 v4, v4
	v_mul_lo_u32 v5, v5, v4
	v_mul_hi_u32 v5, v4, v5
	v_add_u32_e32 v4, v4, v5
	v_mul_hi_u32 v4, v3, v4
	v_mul_lo_u32 v5, v4, v2
	v_sub_u32_e32 v5, v3, v5
	v_cmp_ge_u32_e32 vcc, v5, v2
	v_add_u32_e32 v6, 1, v4
	v_add_u32_e32 v3, 1, v3
	v_cndmask_b32_e32 v4, v4, v6, vcc
	v_sub_u32_e32 v6, v5, v2
	v_cndmask_b32_e32 v5, v5, v6, vcc
	v_cmp_ge_u32_e32 vcc, v5, v2
	v_add_u32_e32 v5, 1, v4
	s_nop 0
	v_cndmask_b32_e32 v4, v4, v5, vcc
	v_mul_lo_u32 v5, v2, v4
	v_add_u32_e32 v2, v5, v2
	v_cmp_ne_u32_e32 vcc, v3, v2
	v_mov_b64_e32 v[2:3], s[6:7]
	s_and_saveexec_b64 s[38:39], vcc
	s_cbranch_execz .LBB0_1060
	v_readlane_b32 s6, v239, 58
	v_readlane_b32 s7, v239, 59
	s_mov_b64 s[42:43], 0
	s_nop 3
	global_load_dword v2, v66, s[6:7] sc1
	s_waitcnt vmcnt(0)
	v_cmp_eq_u32_e32 vcc, v2, v4
	s_and_saveexec_b64 s[40:41], vcc
	s_cbranch_execz .LBB0_1059
	s_mov_b32 s23, 1
	s_branch .LBB0_1052

; __device__ __forceinline__ void xcc_local_barrier(unsigned* bar2, unsigned x, unsigned nloc, unsigned* tmobar) {
;     ...
;         __builtin_amdgcn_fence(__ATOMIC_ACQUIRE, "agent");
;         asm volatile("s_waitcnt vmcnt(0)" ::: "memory");
.LBB0_1062:
	s_or_b64 exec, exec, s[38:39]
	s_waitcnt vmcnt(0)
	s_waitcnt vmcnt(0)
